# SB window: K tiles fetched as full 128-B rows into an XOR-swizzled row-major LDS image (was 16-B chunks of 64 rows per DMA piece)
# speedup vs baseline: 1.0038x; 1.0038x over previous
; __device__ __forceinline__ void sb_unit(int b, int hh, int qb, const bf16_t* Q, const bf16_t* __restrict__ K, const bf16_t* __restrict__ V, bf16_t* O, float* SS, LAS3 unsigned char* shm) {
;     ...
;     const int tid = threadIdx.x, lane = tid & 63, r32 = lane & 31, hi = lane >> 5; const int wid = __builtin_amdgcn_readfirstlane(tid >> 6);
;     const long rowbase = (long)b * SEQ; const int q0 = qb * 256, qw0 = q0 + wid * 32;
;     const bf16_t* Qw = Q + (rowbase + qw0) * DM + hh * 64;
;     const bf16_t* Kh = K + rowbase * DM + hh * 64; const bf16_t* Vh = V + rowbase * DM + hh * 64;
;     const unsigned lds0 = (unsigned)(uintptr_t)shm;
;     const bf16_t* ksrc = Kh + (long)lane * DM + wid * 8;
;     const bf16_t* vsrc = Vh + (long)(16 * (wid & 3) + (lane >> 2)) * DM + (wid >> 2) * 32 + (lane & 3) * 8;
;     const int T_hi = 4 * qb + 3, T_lo = (4 * qb - 3 > 0) ? 4 * qb - 3 : 0;
;     for (int t = T_hi; t >= T_lo; --t) { glds16(ksrc + (long)t * KVB * DM, (unsigned)__builtin_amdgcn_readfirstlane(lds0 + (t - T_lo) * SLOTB + wid * 1024));
;                                          glds16(vsrc + (long)t * KVB * DM, (unsigned)__builtin_amdgcn_readfirstlane(lds0 + WV + (t - T_lo) * SLOTB + wid * 1024)); }
; __global__ void __launch_bounds__(NWAVES * 64, 2) fwd_megakernel(Args args) {
;     ...
;             const unsigned idx = qw[0];
;             if (idx >= 2048u) break;
;             if (idx < 1024u) { const int qb = 31 - (int)(idx >> 5), bh = (int)(idx & 31);
;                 att::fox_unit(bh >> 3, bh & 7, qb, QB, KB, VB, OB, F2, FS3, CTL + 64, SS, lds); }
;             else { const int u = (int)idx - 1024, qb = 31 - (u >> 5), bh = u & 31;
;                 att::sb_unit(bh >> 3, 8 + (bh & 7), qb, QB, KB, VB, OB, SS, lds); }
.LBB0_363:
	s_or_b64 exec, exec, s[0:1]
	s_waitcnt lgkmcnt(0)
	s_barrier
	ds_read_b32 v2, v173
	s_movk_i32 s0, 0x7ff
	s_waitcnt lgkmcnt(0)
	v_cmp_lt_u32_e32 vcc, s0, v2
	v_readfirstlane_b32 s77, v2
	s_mov_b64 s[0:1], -1
	s_cbranch_vccnz .LBB0_358
	s_cmpk_gt_u32 s77, 0x3ff
	s_cbranch_scc0 .LBB0_408
	s_add_i32 s0, s77, 0xfffffc00
	s_lshr_b32 s2, s0, 5
	s_bfe_u32 s1, s77, 0x20003
	s_and_b32 s84, s77, 7
	v_readfirstlane_b32 s3, v178
	s_sub_i32 s0, 31, s2
	s_or_b32 s6, s84, 8
	s_lshr_b32 s5, s3, 6
	s_lshl_b32 s7, s1, 24
	s_add_u32 s10, s88, s7
	s_addc_u32 s11, s95, 0
	s_lshl_b32 s12, s6, 7
	s_add_u32 s10, s10, s12
	s_addc_u32 s11, s11, 0
	s_add_u32 s7, s96, s7
	s_addc_u32 s13, s97, 0
	s_add_u32 s12, s7, s12
	v_mov_b32_e32 v153, v3
	s_addc_u32 s13, s13, 0
	v_lshl_add_u64 v[4:5], s[10:11], 0, v[152:153]
	s_lshl_b32 s80, s5, 4
	s_lshr_b32 s3, s3, 2
	v_lshl_add_u64 v[98:99], v[4:5], 0, s[80:81]
	v_and_b32_e32 v246, 63, v178
	v_lshrrev_b32_e32 v247, 4, v246
	s_and_b32 s98, s5, 1
	s_lshl_b32 s98, s98, 2
	v_add_u32_e32 v247, s98, v247
	v_and_b32_e32 v239, 7, v246
	v_xor_b32_e32 v247, v239, v247
	v_lshlrev_b32_e32 v247, 4, v247
	v_lshrrev_b32_e32 v239, 3, v246
	v_lshl_add_u32 v247, v239, 11, v247
	s_lshl_b32 s98, s5, 14
	v_add_u32_e32 v244, s98, v247
	v_mov_b32_e32 v245, 0
	v_lshl_add_u64 v[244:245], s[10:11], 0, v[244:245]
	v_and_b32_e32 v247, 31, v246
	v_lshrrev_b32_e32 v246, 5, v246
	v_bfe_u32 v236, v247, 1, 3
	v_lshlrev_b32_e32 v238, 4, v247
	v_lshl_add_u32 v238, v246, 10, v238
	v_lshlrev_b32_e32 v237, 7, v247
	v_sub_u32_e32 v237, v237, v238
	v_add_u32_e32 v239, 0, v246
	v_xor_b32_e32 v239, v239, v236
	v_lshl_add_u32 v240, v239, 4, v237
	v_add_u32_e32 v239, 2, v246
	v_xor_b32_e32 v239, v239, v236
	v_lshl_add_u32 v241, v239, 4, v237
	v_add_u32_e32 v239, 4, v246
	v_xor_b32_e32 v239, v239, v236
	v_lshl_add_u32 v242, v239, 4, v237
	v_add_u32_e32 v239, 6, v246
	v_xor_b32_e32 v239, v239, v236
	v_lshl_add_u32 v243, v239, 4, v237
	v_and_or_b32 v2, s3, 48, v135
	s_and_b32 s80, s3, 0x3fffffc0
	s_lshl_b32 s3, s0, 2
	v_lshlrev_b32_e32 v2, 10, v2
	s_or_b32 s7, s3, 3
	s_add_i32 s3, s3, -3
	v_lshl_add_u64 v[4:5], v[2:3], 1, s[12:13]
	s_cmp_lg_u32 s2, 31
	v_lshl_add_u64 v[4:5], v[4:5], 0, s[80:81]
	v_mov_b32_e32 v155, v3
	s_cselect_b32 s3, s3, 0
	s_cmp_lt_i32 s7, s3
	v_lshl_add_u64 v[100:101], v[4:5], 0, v[154:155]
	s_cbranch_scc1 .LBB0_368
	s_lshl_b32 s7, s5, 10
	s_lshl_b32 s10, s2, 2
	s_sub_i32 s80, 0x80, s10
	s_add_i32 s7, s7, 0
	s_lshl_b32 s10, s3, 13
	s_sub_i32 s7, s7, s10
	s_lshl_b32 s10, s2, 15
	s_sub_i32 s7, s7, s10
	s_add_i32 s7, s7, 0x10c000
.LBB0_367:
	s_add_i32 s80, s80, -1
	s_lshl_b64 s[10:11], s[80:81], 17
	s_add_i32 s12, s7, 0xffff2000
	v_lshl_add_u64 v[4:5], v[244:245], 0, s[10:11]
	v_lshl_add_u64 v[6:7], v[100:101], 0, s[10:11]
	s_mov_b32 s10, m0
	s_mov_b32 m0, s12
	s_nop 0
	global_load_lds_dwordx4 v[4:5], off
	s_mov_b32 m0, s10
	s_nop 0
	s_mov_b32 s10, m0
	s_mov_b32 m0, s7
	s_nop 0
	global_load_lds_dwordx4 v[6:7], off
	s_mov_b32 m0, s10
	s_addk_i32 s7, 0xe000
	s_cmp_le_i32 s80, s3
	s_cbranch_scc0 .LBB0_367

; #define LAS3 __attribute__((address_space(3)))
; __device__ __forceinline__ void sb_tile(const LAS3 unsigned char* kp, const LAS3 unsigned char* vp, int jt, int qw0, int r32, int hi, const bf16x8 (&qr)[4], float& carry, f32x16& o0, f32x16& o1) {
;     f32x16 p0, p1;
; #pragma unroll
;     for (int r = 0; r < 16; ++r) { p0[r] = 0.f; p1[r] = 0.f; }
; #pragma unroll
;     for (int d0 = 0; d0 < 4; ++d0) {
;         const bf16x8 k0 = *(const LAS3 bf16x8*)(kp + d0 * 2048), k1 = *(const LAS3 bf16x8*)(kp + d0 * 2048 + 512);
;         p0 = __builtin_amdgcn_mfma_f32_32x32x16_bf16(k0, qr[d0], p0, 0, 0, 0);
;         p1 = __builtin_amdgcn_mfma_f32_32x32x16_bf16(k1, qr[d0], p1, 0, 0, 0);
;     }
; #pragma unroll
;     for (int r = 0; r < 16; ++r) { p0[r] = __builtin_amdgcn_rcpf(1.0f + __builtin_amdgcn_exp2f(p0[r])); p1[r] = __builtin_amdgcn_rcpf(1.0f + __builtin_amdgcn_exp2f(p1[r])); }
.LBB0_370:
	v_add_u32_e32 v4, s7, v104
	v_add_u32_e32 v232, v4, v240
	v_add_u32_e32 v233, v4, v241
	v_add_u32_e32 v234, v4, v242
	v_add_u32_e32 v235, v4, v243
	ds_read_b128 v[6:9], v232
	s_cmp_lt_u32 s6, s86
	s_waitcnt lgkmcnt(0)
	v_mfma_f32_32x32x16_bf16 v[50:65], v[6:9], v[82:85], 0
	ds_read_b128 v[6:9], v232 offset:4096
	s_waitcnt lgkmcnt(0)
	v_mfma_f32_32x32x16_bf16 v[66:81], v[6:9], v[82:85], 0
	ds_read_b128 v[6:9], v233
	s_waitcnt lgkmcnt(0)
	v_mfma_f32_32x32x16_bf16 v[50:65], v[6:9], v[86:89], v[50:65]
	ds_read_b128 v[6:9], v233 offset:4096
	s_waitcnt lgkmcnt(0)
	v_mfma_f32_32x32x16_bf16 v[66:81], v[6:9], v[86:89], v[66:81]
	ds_read_b128 v[6:9], v234
	s_waitcnt lgkmcnt(0)
	v_mfma_f32_32x32x16_bf16 v[50:65], v[6:9], v[90:93], v[50:65]
	ds_read_b128 v[6:9], v234 offset:4096
	s_waitcnt lgkmcnt(0)
	v_mfma_f32_32x32x16_bf16 v[66:81], v[6:9], v[90:93], v[66:81]
	ds_read_b128 v[6:9], v235
	s_waitcnt lgkmcnt(0)
	v_mfma_f32_32x32x16_bf16 v[50:65], v[6:9], v[94:97], v[50:65]
	ds_read_b128 v[6:9], v235 offset:4096
	s_waitcnt lgkmcnt(0)
	v_mfma_f32_32x32x16_bf16 v[66:81], v[6:9], v[94:97], v[66:81]
	s_nop 8
	v_exp_f32_e32 v4, v50
	s_nop 0
	v_add_f32_e32 v4, 1.0, v4
	v_rcp_f32_e32 v14, v4
	v_exp_f32_e32 v4, v51
	v_exp_f32_e32 v6, v66
	v_exp_f32_e32 v7, v67
	v_exp_f32_e32 v11, v71
	v_add_f32_e32 v4, 1.0, v4
	v_rcp_f32_e32 v15, v4
	v_exp_f32_e32 v4, v52
	v_add_f32_e32 v7, 1.0, v7
	v_rcp_f32_e32 v8, v7
	v_exp_f32_e32 v7, v68
	v_add_f32_e32 v4, 1.0, v4
	v_rcp_f32_e32 v66, v4
	v_exp_f32_e32 v4, v53
	v_add_f32_e32 v7, 1.0, v7
	v_rcp_f32_e32 v9, v7
	v_exp_f32_e32 v7, v69
	v_add_f32_e32 v4, 1.0, v4
	v_rcp_f32_e32 v67, v4
	v_exp_f32_e32 v4, v54
	v_add_f32_e32 v11, 1.0, v11
	v_rcp_f32_e32 v12, v11
	v_exp_f32_e32 v11, v72
	v_add_f32_e32 v4, 1.0, v4
	v_rcp_f32_e32 v16, v4
	v_exp_f32_e32 v4, v55
	v_exp_f32_e32 v55, v76
	v_add_f32_e32 v11, 1.0, v11
	v_exp_f32_e32 v10, v70
	v_add_f32_e32 v4, 1.0, v4
	v_rcp_f32_e32 v52, v4
	v_exp_f32_e32 v4, v56
	v_add_f32_e32 v55, 1.0, v55
	v_rcp_f32_e32 v68, v55
	v_rcp_f32_e32 v13, v11
	v_add_f32_e32 v4, 1.0, v4
	v_rcp_f32_e32 v53, v4
	v_exp_f32_e32 v4, v57
	v_exp_f32_e32 v11, v73
	v_exp_f32_e32 v50, v74
	v_exp_f32_e32 v51, v75
	v_add_f32_e32 v4, 1.0, v4
	v_rcp_f32_e32 v17, v4
	v_exp_f32_e32 v4, v58
	v_exp_f32_e32 v58, v77
	v_add_f32_e32 v6, 1.0, v6
	v_add_f32_e32 v7, 1.0, v7
	v_add_f32_e32 v4, 1.0, v4
	v_rcp_f32_e32 v54, v4
	v_exp_f32_e32 v4, v59
	v_add_f32_e32 v58, 1.0, v58
	v_exp_f32_e32 v59, v78
	v_add_f32_e32 v10, 1.0, v10
	v_add_f32_e32 v4, 1.0, v4
	v_rcp_f32_e32 v56, v4
	v_exp_f32_e32 v4, v60
	v_add_f32_e32 v59, 1.0, v59
	v_rcp_f32_e32 v69, v59
	v_exp_f32_e32 v60, v79
	v_add_f32_e32 v4, 1.0, v4
	v_rcp_f32_e32 v57, v4
	v_exp_f32_e32 v4, v61
	v_add_f32_e32 v60, 1.0, v60
	v_exp_f32_e32 v61, v80
	v_add_f32_e32 v11, 1.0, v11
	v_add_f32_e32 v4, 1.0, v4
	v_rcp_f32_e32 v55, v4
	v_exp_f32_e32 v4, v62
	v_rcp_f32_e32 v62, v58
	v_add_f32_e32 v61, 1.0, v61
	v_add_f32_e32 v50, 1.0, v50
	v_add_f32_e32 v4, 1.0, v4
	v_rcp_f32_e32 v58, v4
	v_exp_f32_e32 v4, v63
	v_rcp_f32_e32 v63, v60
	v_add_f32_e32 v51, 1.0, v51
	v_rcp_f32_e32 v6, v6
	v_add_f32_e32 v4, 1.0, v4
	v_rcp_f32_e32 v59, v4
	v_exp_f32_e32 v4, v64
	v_rcp_f32_e32 v64, v61
	v_rcp_f32_e32 v7, v7
	v_rcp_f32_e32 v10, v10
	v_add_f32_e32 v4, 1.0, v4
	v_rcp_f32_e32 v60, v4
	v_exp_f32_e32 v4, v65
	v_exp_f32_e32 v65, v81
	v_rcp_f32_e32 v11, v11
	v_rcp_f32_e32 v50, v50
	v_add_f32_e32 v4, 1.0, v4
	v_rcp_f32_e32 v61, v4
	v_add_f32_e32 v4, 1.0, v65
	v_rcp_f32_e32 v51, v51
	v_rcp_f32_e32 v65, v4
	s_cbranch_scc1 .LBB0_372
; __device__ __forceinline__ void sb_tile(const LAS3 unsigned char* kp, const LAS3 unsigned char* vp, int jt, int qw0, int r32, int hi, const bf16x8 (&qr)[4], float& carry, f32x16& o0, f32x16& o1) {
;     ...
;     if (64 * jt + 63 > qw0 - 1) { const int kb_ = 64 * jt + 4 * hi - (qw0 + r32);
; #pragma unroll
;         for (int r = 0; r < 16; ++r) { const int cr = (r & 3) + 8 * (r >> 2); if (kb_ + cr >= 0) p0[r] = 1.0f; if (kb_ + cr + 32 >= 0) p1[r] = 1.0f; } }
	s_movk_i32 s11, 0xffdd
	v_cmp_lt_i32_e64 s[12:13], s11, v2
	s_movk_i32 s11, 0xffdc
	v_cmp_lt_i32_e64 s[14:15], s11, v2
	s_movk_i32 s11, 0xffd7
	v_cmp_lt_i32_e64 s[16:17], s11, v2
	s_movk_i32 s11, 0xffd6
	v_cmp_lt_i32_e64 s[18:19], s11, v2
	s_movk_i32 s11, 0xffd5
	v_cmp_lt_i32_e64 s[20:21], s11, v2
	s_movk_i32 s11, 0xffd4
	v_cmp_lt_i32_e64 s[22:23], s11, v2
	s_movk_i32 s11, 0xffcf
	v_cmp_lt_i32_e64 s[24:25], s11, v2
	s_movk_i32 s11, 0xffef
	v_cmp_gt_i32_e64 s[56:57], s11, v2
	s_movk_i32 s11, 0xffce
	v_cmp_lt_i32_e64 s[26:27], s11, v2
	s_movk_i32 s11, 0xffee
	v_cmp_gt_i32_e64 s[58:59], s11, v2
	s_movk_i32 s11, 0xffcd
	v_cmp_lt_i32_e64 s[28:29], s11, v2
	s_movk_i32 s11, 0xffed
	v_cmp_gt_i32_e64 s[60:61], s11, v2
	s_movk_i32 s11, 0xffcc
	v_cmp_lt_i32_e64 s[30:31], s11, v2
	s_movk_i32 s11, 0xffe8
	v_cmp_gt_i32_e64 s[62:63], s11, v2
	s_movk_i32 s11, 0xffc7
	v_cmp_lt_i32_e64 s[34:35], s11, v2
	s_movk_i32 s11, 0xffe7
	v_cmp_gt_i32_e64 s[64:65], s11, v2
	s_movk_i32 s11, 0xffc6
	v_cmp_lt_i32_e64 s[36:37], s11, v2
	s_movk_i32 s11, 0xffe6
	v_cmp_gt_i32_e64 s[66:67], s11, v2
	s_movk_i32 s11, 0xffc5
	v_cmp_lt_i32_e64 s[68:69], s11, v2
	s_movk_i32 s11, 0xffe5
	v_cmp_gt_i32_e64 s[70:71], s11, v2
	s_or_b64 s[66:67], s[70:71], s[66:67]
	s_or_b64 s[64:65], s[66:67], s[64:65]
	s_or_b64 s[62:63], s[64:65], s[62:63]
	s_or_b64 s[60:61], s[62:63], s[60:61]
	s_or_b64 s[58:59], s[60:61], s[58:59]
	v_cmp_gt_i32_e64 s[54:55], -16, v2
	s_or_b64 s[56:57], s[58:59], s[56:57]
	v_cmp_gt_i32_e64 s[52:53], -11, v2
	s_or_b64 s[54:55], s[56:57], s[54:55]
	v_cmp_gt_i32_e64 s[50:51], -10, v2
	s_or_b64 s[52:53], s[54:55], s[52:53]
	v_cmp_gt_i32_e64 s[48:49], -9, v2
	s_or_b64 s[50:51], s[52:53], s[50:51]
	v_cmp_gt_i32_e64 s[46:47], -8, v2
	s_or_b64 s[48:49], s[50:51], s[48:49]
	v_cmp_gt_i32_e64 s[44:45], -3, v2
	s_or_b64 s[46:47], s[48:49], s[46:47]
	v_cmp_gt_i32_e64 s[42:43], -2, v2
	s_or_b64 s[44:45], s[46:47], s[44:45]
	v_cmp_gt_i32_e64 s[40:41], -1, v2
	s_or_b64 s[42:43], s[44:45], s[42:43]
	v_cmp_gt_i32_e64 s[38:39], 0, v2
	s_or_b64 s[40:41], s[42:43], s[40:41]
	s_or_b64 s[38:39], s[40:41], s[38:39]
	s_movk_i32 s11, 0xffc4
	v_cndmask_b32_e64 v14, 1.0, v14, s[38:39]
	v_cmp_lt_i32_e64 s[38:39], s11, v2
	s_movk_i32 s0, 0xffdf
	v_cmp_lt_i32_e32 vcc, s0, v2
	v_cndmask_b32_e64 v65, v65, 1.0, s[38:39]
	s_and_b64 s[38:39], s[38:39], s[68:69]
	s_and_b64 s[36:37], s[38:39], s[36:37]
	s_and_b64 s[34:35], s[36:37], s[34:35]
	s_and_b64 s[30:31], s[34:35], s[30:31]
	s_and_b64 s[28:29], s[30:31], s[28:29]
	s_and_b64 s[26:27], s[28:29], s[26:27]
	s_and_b64 s[24:25], s[26:27], s[24:25]
	s_and_b64 s[22:23], s[24:25], s[22:23]
	s_and_b64 s[20:21], s[22:23], s[20:21]
	s_and_b64 s[18:19], s[20:21], s[18:19]
	s_and_b64 s[16:17], s[18:19], s[16:17]
	s_movk_i32 s0, 0xffde
	s_and_b64 s[14:15], s[16:17], s[14:15]
	v_cmp_lt_i32_e64 s[0:1], s0, v2
	s_and_b64 s[12:13], s[14:15], s[12:13]
	s_and_b64 s[0:1], s[12:13], s[0:1]
	v_cndmask_b32_e64 v8, v8, 1.0, s[0:1]
	s_and_b64 s[0:1], s[0:1], vcc
	v_cndmask_b32_e64 v61, 1.0, v61, s[70:71]
	v_cndmask_b32_e64 v60, 1.0, v60, s[66:67]
	v_cndmask_b32_e64 v59, 1.0, v59, s[64:65]
	v_cndmask_b32_e64 v58, 1.0, v58, s[62:63]
	v_cndmask_b32_e64 v55, 1.0, v55, s[60:61]
	v_cndmask_b32_e64 v57, 1.0, v57, s[58:59]
	v_cndmask_b32_e64 v56, 1.0, v56, s[56:57]
	v_cndmask_b32_e64 v54, 1.0, v54, s[54:55]
	v_cndmask_b32_e64 v17, 1.0, v17, s[52:53]
	v_cndmask_b32_e64 v53, 1.0, v53, s[50:51]
	v_cndmask_b32_e64 v52, 1.0, v52, s[48:49]
	v_cndmask_b32_e64 v16, 1.0, v16, s[46:47]
	v_cndmask_b32_e64 v67, 1.0, v67, s[44:45]
	v_cndmask_b32_e64 v66, 1.0, v66, s[42:43]
	v_cndmask_b32_e64 v15, 1.0, v15, s[40:41]
	v_cndmask_b32_e64 v64, v64, 1.0, s[38:39]
	v_cndmask_b32_e64 v63, v63, 1.0, s[36:37]
	v_cndmask_b32_e64 v69, v69, 1.0, s[34:35]
	v_cndmask_b32_e64 v62, v62, 1.0, s[30:31]
	v_cndmask_b32_e64 v68, v68, 1.0, s[28:29]
	v_cndmask_b32_e64 v51, v51, 1.0, s[26:27]
	v_cndmask_b32_e64 v50, v50, 1.0, s[24:25]
	v_cndmask_b32_e64 v11, v11, 1.0, s[22:23]
	v_cndmask_b32_e64 v13, v13, 1.0, s[20:21]
	v_cndmask_b32_e64 v12, v12, 1.0, s[18:19]
	v_cndmask_b32_e64 v10, v10, 1.0, s[16:17]
	v_cndmask_b32_e64 v7, v7, 1.0, s[14:15]
	v_cndmask_b32_e64 v9, v9, 1.0, s[12:13]
	v_cndmask_b32_e64 v6, v6, 1.0, s[0:1]
